# Ph6 next-group xn rows moved to the workgroups with one FFN-up unit less and no sample unit
# speedup vs baseline: 1.0080x; 1.0080x over previous
;     DI bool next(int i, Unit& u) const {
;         const long L = (long)i * G + c; if (L >= nwg) return false;
;         int wgid = (int)L; { const int q = nwg / NXCD, r = nwg % NXCD, xcd = wgid % NXCD, off = wgid / NXCD; wgid = (xcd < r ? xcd * (q + 1) : r * (q + 1) + (xcd - r) * q) + off; }
;         const int nig = WGM * nN, gid = wgid / nig, fm = gid * WGM, gsz = (nM - fm) < WGM ? (nM - fm) : WGM;
;         u.pm = fm + ((wgid % nig) % gsz); u.pn = (wgid % nig) / gsz; return true;
; __global__ void __launch_bounds__(512, 2) fwd_mega(Params P) {
;     ...
;         if (g + 1 < NGRP && bid >= G / 2) { const size_t n0 = (size_t)(g + 1) * MG;
;             const int st_ = (G - G / 2) * 8;
.LBB0_269:
	v_readlane_b32 s40, v252, 7
	s_and_b32 s0, s33, 0xf8
	s_ashr_i32 s1, s40, 5
	s_add_i32 s0, s0, s1
	s_cmpk_eq_i32 s52, 0x100
	s_cselect_b32 s42, s0, s40
	s_not_b32 s3, s42
	s_cmpk_lt_i32 s42, 0x6c0
	s_cselect_b64 s[0:1], -1, 0
	v_readlane_b32 s41, v252, 8
	v_writelane_b32 v252, s0, 19
	s_ashr_i32 s43, s42, 31
	s_add_i32 s18, s52, s3
	v_writelane_b32 v252, s1, 20
	s_lshr_b32 s0, s43, 29
	s_add_i32 s0, s42, s0
	s_ashr_i32 s14, s0, 3
	s_and_b32 s0, s0, -8
	s_sub_i32 s15, s42, s0
	s_cmp_lt_i32 s18, 54
	s_cselect_b64 s[0:1], -1, 0
	v_writelane_b32 v252, s0, 21
	s_ashr_i32 s19, s18, 31
	v_mov_b32_e32 v224, 1
	v_writelane_b32 v252, s1, 22
	s_lshr_b32 s0, s19, 29
	s_add_i32 s0, s18, s0
	s_ashr_i32 s13, s0, 3
	s_and_b32 s0, s0, -8
	s_sub_i32 s22, s18, s0
	s_mul_i32 s0, s22, 6
	s_add_i32 s4, s0, 6
	s_cmpk_lt_i32 s42, 0x100
	s_cselect_b64 s[6:7], -1, 0
	s_lshl_b32 s2, s15, 5
	v_writelane_b32 v252, s6, 23
	s_cmpk_lt_i32 s18, 0x80
	v_mov_b32_e32 v225, 0x358637bd
	v_writelane_b32 v252, s7, 24
	s_cselect_b64 s[6:7], -1, 0
	s_lshl_b32 s20, s22, 4
	v_writelane_b32 v252, s6, 25
	s_cmp_lt_i32 s18, 8
	v_mbcnt_hi_u32_b32 v226, -1, v220
	v_writelane_b32 v252, s7, 26
	s_cselect_b64 s[6:7], -1, 0
	s_lshr_b32 s1, s22, 31
	s_lshl_b32 s1, s22, s1
	s_add_i32 s1, s1, s13
	s_ashr_i32 s5, s1, 31
	s_lshr_b32 s5, s5, 27
	v_writelane_b32 v252, s6, 27
	s_add_i32 s5, s1, s5
	v_mov_b64_e32 v[222:223], 0x100
	v_writelane_b32 v252, s7, 28
	s_ashr_i32 s6, s5, 5
	s_lshl_b32 s6, s6, 3
	s_sub_i32 s7, 2, s6
	s_andn2_b32 s5, s5, 31
	s_min_u32 s7, s7, 8
	s_sub_i32 s12, s1, s5
	s_cmpk_lt_i32 s42, 0x180
	s_cselect_b64 s[8:9], -1, 0
	v_writelane_b32 v252, s8, 29
	s_cmp_lt_i32 s18, 12
	v_mov_b32_e32 v227, 0x7ffff
	v_writelane_b32 v252, s9, 30
	s_cselect_b64 s[8:9], -1, 0
	v_writelane_b32 v252, s8, 31
	s_add_i32 s5, s22, 4
	s_lshl_b32 s1, s22, 1
	v_writelane_b32 v252, s9, 32
	s_lshl_b32 s8, s22, 2
	s_add_i32 s8, s5, s8
	s_cmp_lt_i32 s22, 4
	s_cselect_b32 s1, s1, s5
	s_cselect_b32 s16, s0, s8
	s_add_i32 s1, s1, s13
	s_mul_hi_i32 s0, s1, 0x2aaaaaab
	s_lshr_b32 s5, s0, 31
	s_ashr_i32 s0, s0, 3
	s_add_i32 s0, s0, s5
	s_lshl_b32 s9, s0, 3
	s_mul_i32 s5, s0, 48
	s_sub_i32 s0, 2, s9
	s_min_u32 s10, s0, 8
	s_sub_i32 s11, s1, s5
	s_cmpk_lt_i32 s40, 0x100
	s_cselect_b64 s[0:1], -1, 0
	s_lshr_b32 s33, s46, 7
	s_lshl_b32 s86, s47, 5
	s_cmpk_lt_u32 s46, 0x200
	v_writelane_b32 v252, s0, 33
	s_cselect_b64 s[84:85], -1, 0
	s_cmpk_lt_i32 s40, 0x200
	v_writelane_b32 v252, s1, 34
	s_cselect_b64 s[0:1], -1, 0
	v_writelane_b32 v252, s0, 35
	s_cmpk_lt_i32 s40, 0x400
	v_mov_b32_e32 v228, 0xc00
	v_writelane_b32 v252, s1, 36
	s_cselect_b64 s[0:1], -1, 0
	v_writelane_b32 v252, s0, 37
	v_mov_b32_e32 v229, 0xf149f2ca
	v_mov_b32_e32 v221, 0x22000
	v_writelane_b32 v252, s1, 38
	s_and_b32 s0, s52, 7
	s_cmp_lg_u32 s0, 0
	s_cselect_b64 s[0:1], -1, 0
	s_lshl_b32 s5, s47, 1
	s_and_b32 s8, s5, 2
	s_lshl_b32 s5, s47, 4
	s_and_b32 s5, s5, 0x3fffffe0
	v_writelane_b32 v252, s5, 39
	s_lshl_b32 s5, s8, 1
	s_lshl_b32 s8, s8, 5
	v_writelane_b32 v252, s8, 40
	s_or_b32 s8, s8, 32
	s_cmpk_lt_i32 s18, 0x220
	v_writelane_b32 v252, s8, 41
	s_cselect_b64 s[24:25], -1, 0
	s_not_b32 s8, s40
	s_add_i32 s39, s52, s8
	v_writelane_b32 v252, s24, 42
	s_cmpk_lt_i32 s39, 0x100
	s_movk_i32 s78, 0x440
	v_writelane_b32 v252, s25, 43
	s_cselect_b64 s[24:25], -1, 0
	s_cmp_lt_u32 s46, 64
	v_writelane_b32 v252, s24, 44
	s_cselect_b64 s[94:95], -1, 0
	s_cmp_gt_u32 s46, 63
	v_writelane_b32 v252, s25, 45
	s_cselect_b64 s[24:25], -1, 0
	v_writelane_b32 v252, s24, 46
	s_cmpk_lt_i32 s42, 0x580
	s_movk_i32 s79, 0x3600
	v_writelane_b32 v252, s25, 47
	s_cselect_b64 s[24:25], -1, 0
	s_lshr_b32 s8, s52, 31
	s_add_i32 s8, s52, s8
	s_ashr_i32 s8, s8, 1
	v_writelane_b32 v252, s24, 48
	s_cmp_lt_i32 s42, s8
	s_mov_b32 s65, 0x800000
	v_writelane_b32 v252, s25, 49
	s_cselect_b64 s[24:25], -1, 0
	s_sub_i32 s17, s52, s8
	s_lshl_b32 s21, s17, 3
	s_sub_i32 s17, s40, s8
	s_lshl_b32 s17, s17, 3
	s_add_i32 s17, s17, s47
	v_writelane_b32 v252, s24, 50
	s_cmpk_lt_i32 s17, 0x4000
	s_mov_b32 s91, 0
	v_writelane_b32 v252, s25, 51
	s_cselect_b64 s[24:25], -1, 0
	v_writelane_b32 v252, s24, 52
	s_ashr_i32 s17, s21, 31
	s_mov_b64 s[56:57], 0x20000
	v_writelane_b32 v252, s25, 53
	v_writelane_b32 v252, s21, 54
	v_writelane_b32 v252, s17, 55
	v_writelane_b32 v252, s18, 56
	s_cmp_lt_i32 s18, 44
	s_mul_i32 s17, s15, 33
	v_writelane_b32 v252, s19, 57
	s_cselect_b64 s[18:19], -1, 0
	v_writelane_b32 v252, s18, 58
	s_cmp_lt_i32 s15, 0
	s_cselect_b32 s21, s17, s2
	v_writelane_b32 v252, s19, 59
	s_movk_i32 s18, 0xd9
	s_cselect_b32 s18, s18, 0xd8
	s_mul_i32 s18, s15, s18
	s_movk_i32 s2, 0xb1
	s_cselect_b32 s23, 49, 48
	s_cselect_b32 s25, s2, 0xb0
	s_add_i32 s18, s18, s14
	s_mul_hi_i32 s2, s18, 0x4bda12f7
	s_lshr_b32 s17, s2, 31
	s_ashr_i32 s2, s2, 6
	s_add_i32 s2, s2, s17
	s_mul_i32 s17, s2, 0xd8
	s_sub_i32 s17, s18, s17
	s_lshl_b32 s19, s2, 3
	s_bfe_u32 s2, s17, 0x3001c
	s_add_i32 s18, s17, s2
	s_sext_i32_i16 s24, s18
	s_and_b32 s18, s18, 0xfff8
	s_sub_i32 s17, s17, s18
	s_sext_i32_i16 s17, s17
	s_lshr_b32 s2, s24, 3
	s_add_i32 s44, s19, s17
	s_ashr_i32 s17, s24, 3
	v_writelane_b32 v252, s17, 60
	s_cmp_lt_i32 s22, 6
	s_mul_i32 s17, s22, 7
	s_cselect_b32 s4, s17, s4
	s_add_i32 s4, s4, s13
	s_mul_hi_i32 s17, s4, 0x4bda12f7
	s_lshr_b32 s18, s17, 31
	s_ashr_i32 s17, s17, 6
	s_add_i32 s17, s17, s18
	s_add_i32 s21, s21, s14
	s_mul_i32 s19, s17, 0xd8
	s_ashr_i32 s26, s21, 31
	s_sub_i32 s19, s4, s19
	s_lshr_b32 s4, s26, 26
	s_add_i32 s4, s21, s4
	s_ashr_i32 s24, s4, 6
	s_and_b32 s4, s4, 0xffc0
	s_sub_i32 s4, s21, s4
	s_bfe_i32 s27, s4, 0x80000
	s_bfe_u32 s27, s27, 0x3000c
	s_add_i32 s27, s4, s27
;     DI bool next(int i, Unit& u) const {
;         const long L = (long)i * G + c; if (L >= nwg) return false;
;         int wgid = (int)L; { const int q = nwg / NXCD, r = nwg % NXCD, xcd = wgid % NXCD, off = wgid / NXCD; wgid = (xcd < r ? xcd * (q + 1) : r * (q + 1) + (xcd - r) * q) + off; }
;         const int nig = WGM * nN, gid = wgid / nig, fm = gid * WGM, gsz = (nM - fm) < WGM ? (nM - fm) : WGM;
;         u.pm = fm + ((wgid % nig) % gsz); u.pn = (wgid % nig) / gsz; return true;
	s_bfe_i32 s28, s27, 0x80000
	s_and_b32 s27, s27, 0xf8
	s_lshl_b32 s17, s17, 3
	s_sub_i32 s27, s4, s27
	s_sub_i32 s18, 2, s17
	s_lshl_b32 s24, s24, 3
	s_sext_i32_i16 s28, s28
	s_sext_i32_i8 s27, s27
	s_min_u32 s18, s18, 8
	s_lshr_b32 s4, s28, 3
	s_add_i32 s48, s24, s27
	s_ashr_i32 s24, s28, 3
	v_writelane_b32 v252, s24, 61
	s_cmp_lt_i32 s22, 0
	s_mul_i32 s24, s22, 17
	s_cselect_b32 s20, s24, s20
	s_movk_i32 s24, 0x45
	s_cselect_b32 s29, s24, 0x44
	s_add_i32 s20, s20, s13
	s_ashr_i32 s24, s20, 31
	s_lshr_b32 s24, s24, 24
	s_add_i32 s27, s20, s24
	s_and_b32 s24, s27, 0xffffff00
	s_sub_i32 s24, s20, s24
	s_mul_i32 s20, s15, s23
	s_add_i32 s20, s20, s14
	s_mul_hi_i32 s23, s20, 0x2aaaaaab
	s_lshr_b32 s28, s23, 31
	s_ashr_i32 s23, s23, 3
	s_add_i32 s23, s23, s28
	s_mul_i32 s28, s23, 48
	s_sub_i32 s20, s20, s28
	s_bfe_i32 s28, s20, 0x80000
	s_bfe_u32 s28, s28, 0x3000c
	s_add_i32 s30, s20, s28
	s_and_b32 s28, s30, 0xf8
	s_sub_i32 s20, s20, s28
	s_lshl_b32 s23, s23, 3
	s_sext_i32_i8 s20, s20
	s_add_i32 s20, s23, s20
	v_writelane_b32 v252, s20, 62
	s_lshr_b32 s20, s26, 27
	s_add_i32 s23, s21, s20
	s_and_b32 s20, s23, 0xffe0
	s_sub_i32 s20, s21, s20
	s_bfe_i32 s28, s20, 0x80000
	s_bfe_u32 s28, s28, 0x3000c
	s_add_i32 s31, s20, s28
	s_and_b32 s28, s31, 0xf8
	s_sub_i32 s34, s20, s28
	s_lshr_b32 s20, s26, 23
	s_add_i32 s26, s21, s20
	s_and_b32 s20, s26, 0xfffffe00
	s_sub_i32 s20, s21, s20
	s_ashr_i32 s21, s27, 8
	s_lshl_b32 s27, s21, 3
	s_sub_i32 s21, 4, s27
	s_min_u32 s28, s21, 8
	s_bfe_i32 s21, s30, 0x80000
	s_sext_i32_i16 s21, s21
	s_ashr_i32 s21, s21, 3
	v_writelane_b32 v252, s21, 63
	s_ashr_i32 s21, s23, 5
	s_bfe_i32 s23, s31, 0x80000
	s_lshl_b32 s21, s21, 3
	s_sext_i32_i16 s30, s23
	s_sext_i32_i8 s23, s34
	s_add_i32 s50, s21, s23
	s_ashr_i32 s21, s26, 9
	s_lshl_b32 s21, s21, 3
	s_sub_i32 s23, 4, s21
	s_min_u32 s23, s23, 8
	s_ashr_i32 s26, s30, 3
	s_lshr_b32 s30, s30, 3
	s_cmpk_lt_u32 s46, 0x180
	s_mul_i32 s22, s22, s29
	s_cselect_b64 s[70:71], -1, 0
	s_add_i32 s22, s22, s13
	v_writelane_b32 v253, s26, 0
	s_ashr_i32 s26, s22, 31
	s_lshr_b32 s26, s26, 27
	s_add_i32 s26, s22, s26
	s_and_b32 s29, s26, 0xffe0
	s_sub_i32 s29, s22, s29
	s_bfe_i32 s31, s29, 0x80000
	s_bfe_u32 s31, s31, 0x3000c
	s_add_i32 s31, s29, s31
	s_and_b32 s34, s31, 0xf8
	s_sub_i32 s29, s29, s34
	s_mul_hi_i32 s34, s22, 0x78787879
	s_mul_i32 s15, s15, s25
	s_lshr_b32 s35, s34, 31
	s_ashr_i32 s34, s34, 9
	s_add_i32 s15, s15, s14
	s_add_i32 s34, s34, s35
	s_mul_hi_i32 s14, s15, 0x2e8ba2e9
	s_mul_i32 s35, s34, 0x440
	s_lshr_b32 s25, s14, 31
	s_ashr_i32 s14, s14, 5
	s_sub_i32 s22, s22, s35
	s_add_i32 s35, s14, s25
	s_mul_i32 s14, s35, 0xb0
	s_sub_i32 s14, s15, s14
	s_bfe_u32 s15, s14, 0x3001c
	s_add_i32 s36, s14, s15
	s_add_i32 s16, s16, s13
	s_and_b32 s15, s36, 0xfff8
	s_mul_hi_i32 s13, s16, 0x2e8ba2e9
	s_sub_i32 s37, s14, s15
	s_lshr_b32 s14, s13, 31
	s_ashr_i32 s13, s13, 5
	s_add_i32 s38, s13, s14
	s_mul_i32 s13, s38, 0xb0
	s_ashr_i32 s14, s26, 5
	s_bfe_i32 s15, s31, 0x80000
	s_sub_i32 s13, s16, s13
	s_lshl_b32 s14, s14, 3
	s_sext_i32_i16 s15, s15
	s_sext_i32_i8 s16, s29
	s_add_i32 s46, s14, s16
	s_ashr_i32 s14, s15, 3
	v_writelane_b32 v253, s14, 1
	s_lshr_b32 s14, s15, 3
	s_bfe_i64 s[14:15], s[14:15], 0x100000
	s_lshl_b64 s[14:15], s[14:15], 17
	v_writelane_b32 v253, s14, 2
	s_lshl_b32 s25, s34, 3
	s_sext_i32_i16 s16, s37
	v_writelane_b32 v253, s15, 3
	s_sub_i32 s14, 4, s25
	s_min_u32 s26, s14, 8
	s_lshl_b32 s14, s35, 3
	s_sext_i32_i16 s15, s36
	s_add_i32 s36, s14, s16
	s_ashr_i32 s14, s15, 3
	v_writelane_b32 v253, s14, 4
	s_lshr_b32 s14, s15, 3
	s_bfe_i64 s[14:15], s[14:15], 0x100000
	s_lshl_b64 s[14:15], s[14:15], 19
	v_writelane_b32 v253, s14, 5
	s_bfe_i64 s[34:35], s[2:3], 0x100000
	s_lshl_b64 s[34:35], s[34:35], 19
	v_writelane_b32 v253, s15, 6
	v_writelane_b32 v253, s34, 7
	s_bfe_i64 s[30:31], s[30:31], 0x100000
	s_ashr_i32 s47, s46, 31
	v_writelane_b32 v253, s35, 8
	s_bfe_i64 s[34:35], s[4:5], 0x100000
	s_lshl_b64 s[34:35], s[34:35], 19
	v_writelane_b32 v253, s34, 9
	s_mov_b32 s4, s46
	s_ashr_i32 s51, s50, 31
	v_writelane_b32 v253, s35, 10
	s_lshl_b64 s[34:35], s[30:31], 19
	v_writelane_b32 v253, s34, 11
	s_lshl_b64 s[30:31], s[30:31], 17
	s_ashr_i32 s37, s36, 31
	v_writelane_b32 v253, s35, 12
	v_writelane_b32 v253, s30, 13
	v_cvt_f32_ubyte0_e32 v1, s18
	s_ashr_i32 s45, s44, 31
	v_writelane_b32 v253, s31, 14
	v_writelane_b32 v253, s4, 15
	s_lshl_b64 s[30:31], s[46:47], 17
	v_cvt_f32_i32_e32 v0, s19
	v_writelane_b32 v253, s5, 16
	v_writelane_b32 v253, s30, 17
	s_mov_b32 s4, s50
	v_rcp_iflag_f32_e32 v2, v1
	v_writelane_b32 v253, s31, 18
	v_writelane_b32 v253, s4, 19
	s_lshl_b64 s[30:31], s[50:51], 19
	s_ashr_i32 s49, s48, 31
	v_writelane_b32 v253, s5, 20
	v_writelane_b32 v253, s30, 21
	s_mov_b32 s4, s36
	v_mul_f32_e32 v2, v0, v2
	v_writelane_b32 v253, s31, 22
	v_writelane_b32 v253, s4, 23
	s_lshl_b64 s[30:31], s[36:37], 19
	v_trunc_f32_e32 v2, v2
	v_writelane_b32 v253, s5, 24
	v_writelane_b32 v253, s30, 25
	s_mov_b32 s4, s44
	v_fma_f32 v0, -v2, v1, v0
	v_writelane_b32 v253, s31, 26
	v_writelane_b32 v253, s4, 27
	s_lshl_b64 s[30:31], s[44:45], 19
	s_lshl_b32 s14, s38, 3
	v_writelane_b32 v253, s5, 28
	v_writelane_b32 v253, s30, 29
	s_mov_b32 s4, s48
	s_sub_i32 s15, 2, s14
	v_writelane_b32 v253, s31, 30
	v_writelane_b32 v253, s4, 31
	s_lshl_b64 s[30:31], s[48:49], 19
	s_ashr_i32 s2, s19, 30
	v_writelane_b32 v253, s5, 32
	v_writelane_b32 v253, s30, 33
	s_min_u32 s15, s15, 8
	s_or_b32 s2, s2, 1
	v_writelane_b32 v253, s31, 34
	v_cmp_ge_f32_e64 s[30:31], |v0|, v1
	v_cvt_i32_f32_e32 v0, v2
	v_cvt_f32_ubyte0_e32 v1, s28
	v_rcp_iflag_f32_e32 v2, v1
	s_and_b64 s[30:31], s[30:31], exec
;     DI bool next(int i, Unit& u) const {
;         const long L = (long)i * G + c; if (L >= nwg) return false;
;         int wgid = (int)L; { const int q = nwg / NXCD, r = nwg % NXCD, xcd = wgid % NXCD, off = wgid / NXCD; wgid = (xcd < r ? xcd * (q + 1) : r * (q + 1) + (xcd - r) * q) + off; }
;         const int nig = WGM * nN, gid = wgid / nig, fm = gid * WGM, gsz = (nM - fm) < WGM ? (nM - fm) : WGM;
;         u.pm = fm + ((wgid % nig) % gsz); u.pn = (wgid % nig) / gsz; return true;
	v_readfirstlane_b32 s16, v0
	v_cvt_f32_i32_e32 v0, s24
	s_cselect_b32 s2, s2, 0
	s_add_i32 s16, s16, s2
	s_mul_i32 s2, s16, s18
	v_mul_f32_e32 v2, v0, v2
	s_sub_i32 s2, s19, s2
	v_trunc_f32_e32 v2, v2
	s_sext_i32_i16 s2, s2
	v_fma_f32 v0, -v2, v1, v0
	s_add_i32 s2, s17, s2
	v_cmp_ge_f32_e64 s[18:19], |v0|, v1
	v_cvt_i32_f32_e32 v0, v2
	v_writelane_b32 v253, s2, 35
	s_ashr_i32 s2, s24, 30
	s_or_b32 s2, s2, 1
	s_and_b64 s[18:19], s[18:19], exec
	s_cselect_b32 s2, s2, 0
	v_readfirstlane_b32 s4, v0
	s_add_i32 s2, s4, s2
	s_mul_i32 s4, s2, s28
	v_cvt_f32_ubyte0_e32 v1, s7
	s_sub_i32 s4, s24, s4
	v_cvt_f32_i32_e32 v0, s12
	v_rcp_iflag_f32_e32 v2, v1
	s_bfe_i64 s[18:19], s[2:3], 0x100000
	s_sext_i32_i16 s4, s4
	s_lshl_b64 s[18:19], s[18:19], 19
	s_add_i32 s28, s27, s4
	v_writelane_b32 v253, s18, 36
	s_ashr_i32 s29, s28, 31
	v_mul_f32_e32 v2, v0, v2
	v_writelane_b32 v253, s19, 37
	s_mov_b32 s18, s28
	v_writelane_b32 v253, s18, 38
	v_trunc_f32_e32 v2, v2
	v_fma_f32 v0, -v2, v1, v0
	v_writelane_b32 v253, s19, 39
	s_lshl_b64 s[18:19], s[28:29], 19
	v_writelane_b32 v253, s18, 40
	s_ashr_i32 s4, s12, 30
	s_or_b32 s4, s4, 1
	v_writelane_b32 v253, s19, 41
	v_cmp_ge_f32_e64 s[18:19], |v0|, v1
	v_cvt_i32_f32_e32 v0, v2
	s_and_b64 s[18:19], s[18:19], exec
	s_cselect_b32 s4, s4, 0
	v_cvt_f32_ubyte0_e32 v1, s23
	v_readfirstlane_b32 s17, v0
	s_add_i32 s4, s17, s4
	s_mul_i32 s7, s4, s7
	s_sub_i32 s7, s12, s7
	s_sext_i32_i8 s7, s7
	s_add_i32 s18, s6, s7
	s_ashr_i32 s6, s20, 30
	v_cvt_f32_i32_e32 v0, s20
	v_rcp_iflag_f32_e32 v2, v1
	s_or_b32 s12, s6, 1
	s_mov_b32 s6, s18
	s_ashr_i32 s19, s18, 31
	v_writelane_b32 v253, s6, 42
	v_mul_f32_e32 v2, v0, v2
	v_trunc_f32_e32 v2, v2
	v_writelane_b32 v253, s7, 43
	s_lshl_b64 s[6:7], s[18:19], 19
	v_writelane_b32 v253, s6, 44
	v_fma_f32 v0, -v2, v1, v0
	s_sext_i32_i16 s2, s2
	v_writelane_b32 v253, s7, 45
	s_bfe_i64 s[6:7], s[4:5], 0x80000
	s_lshl_b64 s[18:19], s[6:7], 19
	v_writelane_b32 v253, s18, 46
	s_mov_b64 s[74:75], 0x60000
	s_mov_b64 s[88:89], 0x80
	v_writelane_b32 v253, s19, 47
	v_cmp_ge_f32_e64 s[18:19], |v0|, v1
	v_cvt_i32_f32_e32 v0, v2
	s_and_b64 s[18:19], s[18:19], exec
	v_cvt_f32_ubyte0_e32 v1, s10
	s_cselect_b32 s7, s12, 0
	v_readfirstlane_b32 s12, v0
	v_cvt_f32_i32_e32 v0, s11
	v_rcp_iflag_f32_e32 v2, v1
	s_add_i32 s7, s12, s7
	s_mul_i32 s12, s7, s23
	s_sub_i32 s12, s20, s12
	v_mul_f32_e32 v2, v0, v2
	v_trunc_f32_e32 v2, v2
	v_fma_f32 v0, -v2, v1, v0
	v_cmp_ge_f32_e64 s[18:19], |v0|, v1
	v_cvt_i32_f32_e32 v0, v2
	s_sext_i32_i16 s12, s12
	s_add_i32 s12, s21, s12
	v_writelane_b32 v253, s12, 48
	s_ashr_i32 s12, s11, 30
	v_cvt_f32_ubyte0_e32 v1, s26
	s_or_b32 s12, s12, 1
	v_readfirstlane_b32 s17, v0
	v_cvt_f32_i32_e32 v0, s22
	v_rcp_iflag_f32_e32 v2, v1
	s_and_b64 s[18:19], s[18:19], exec
	s_cselect_b32 s12, s12, 0
	s_add_i32 s12, s17, s12
	s_mul_i32 s10, s12, s10
	v_mul_f32_e32 v2, v0, v2
	s_sub_i32 s10, s11, s10
	v_trunc_f32_e32 v2, v2
	s_sext_i32_i8 s10, s10
	v_fma_f32 v0, -v2, v1, v0
	s_add_i32 s9, s9, s10
	v_cmp_ge_f32_e64 s[10:11], |v0|, v1
	v_cvt_i32_f32_e32 v0, v2
	v_writelane_b32 v253, s9, 49
	s_ashr_i32 s9, s22, 30
	s_or_b32 s9, s9, 1
	s_and_b64 s[10:11], s[10:11], exec
	s_cselect_b32 s9, s9, 0
	v_readfirstlane_b32 s10, v0
	s_add_i32 s10, s10, s9
	s_mul_i32 s9, s10, s26
	s_sub_i32 s9, s22, s9
	s_bfe_i64 s[18:19], s[10:11], 0x100000
	s_sext_i32_i16 s9, s9
	s_lshl_b64 s[18:19], s[18:19], 17
	s_add_i32 s20, s25, s9
	v_cvt_f32_ubyte0_e32 v1, s15
	v_writelane_b32 v253, s18, 50
	v_cvt_f32_i32_e32 v0, s13
	v_rcp_iflag_f32_e32 v2, v1
	v_writelane_b32 v253, s19, 51
	s_mov_b32 s18, s20
	s_ashr_i32 s21, s20, 31
	v_writelane_b32 v253, s18, 52
	v_mul_f32_e32 v2, v0, v2
	v_trunc_f32_e32 v2, v2
	v_writelane_b32 v253, s19, 53
	s_lshl_b64 s[18:19], s[20:21], 17
	v_writelane_b32 v253, s18, 54
	s_ashr_i32 s9, s13, 30
	v_fma_f32 v0, -v2, v1, v0
	v_writelane_b32 v253, s19, 55
	v_writelane_b32 v253, s2, 56
	s_sext_i32_i8 s2, s4
	v_writelane_b32 v253, s2, 57
	s_mul_hi_i32 s2, s6, 0x160000
	s_or_b32 s9, s9, 1
	v_cmp_ge_f32_e64 s[18:19], |v0|, v1
	v_writelane_b32 v253, s2, 58
	s_mul_i32 s2, s6, 0x160000
	s_and_b64 s[18:19], s[18:19], exec
	v_writelane_b32 v253, s2, 59
	s_sext_i32_i16 s2, s10
	v_writelane_b32 v253, s2, 60
	s_cselect_b32 s2, s9, 0
	s_lshl_b32 s6, s52, 1
	v_readlane_b32 s10, v252, 0
	s_add_i32 s3, s3, s6
	v_readlane_b32 s11, v252, 1
	v_writelane_b32 v253, s3, 61
	v_cvt_i32_f32_e32 v0, v2
	v_writelane_b32 v253, s10, 62
	s_load_dwordx4 s[20:23], s[10:11], 0xe0
	s_sext_i32_i16 s3, s16
	v_readfirstlane_b32 s4, v0
	s_add_i32 s2, s4, s2
	s_mul_i32 s4, s2, s15
	s_waitcnt lgkmcnt(0)
;     DI bool next(int i, Unit& u) const {
;         const long L = (long)i * G + c; if (L >= nwg) return false;
;         int wgid = (int)L; { const int q = nwg / NXCD, r = nwg % NXCD, xcd = wgid % NXCD, off = wgid / NXCD; wgid = (xcd < r ? xcd * (q + 1) : r * (q + 1) + (xcd - r) * q) + off; }
;         const int nig = WGM * nN, gid = wgid / nig, fm = gid * WGM, gsz = (nM - fm) < WGM ? (nM - fm) : WGM;
;         u.pm = fm + ((wgid % nig) % gsz); u.pn = (wgid % nig) / gsz; return true;
; template <class Epi>
; DI void run_gemm_(LAS unsigned char* lds, const bf16_t* A, int lda, const bf16_t* Bt, int ldb, int M, int N, int K, bool rev, const Epi& E, int wid0) {
;     pg8::Gemm g{A, Bt, M, N, K, lda, ldb}; pg8::StaticOrder S; const int G = (int)gridDim.x;
;     const int bx_ = (G == 256) ? (((int)blockIdx.x & 31) * 8 + ((int)blockIdx.x >> 5)) : (int)blockIdx.x;
;     S.init(M, N, G, rev ? G - 1 - bx_ : bx_);
	v_writelane_b32 v254, s20, 0
	s_sub_i32 s4, s13, s4
	v_writelane_b32 v253, s11, 63
	v_writelane_b32 v254, s21, 1
	v_writelane_b32 v254, s22, 2
	v_writelane_b32 v254, s23, 3
	v_writelane_b32 v254, s3, 4
	s_sext_i32_i16 s3, s7
	v_writelane_b32 v254, s3, 5
	s_sext_i32_i8 s3, s12
	v_writelane_b32 v254, s3, 6
	s_sext_i32_i16 s3, s4
	s_add_i32 s10, s14, s3
	s_sext_i32_i16 s3, s2
	v_writelane_b32 v254, s3, 7
	s_bfe_i64 s[2:3], s[2:3], 0x100000
	s_lshl_b64 s[2:3], s[2:3], 19
	v_writelane_b32 v254, s2, 8
	v_readlane_b32 s6, v252, 13
	v_readlane_b32 s7, v252, 14
	v_writelane_b32 v254, s3, 9
	s_mul_i32 s2, s53, 0x600
	s_mul_hi_u32 s3, s52, 0x600
	s_add_i32 s7, s3, s2
	s_mul_i32 s2, s33, 0x2200
	s_add_i32 s2, s2, 0
	s_add_i32 s2, s2, 0x8800
	v_writelane_b32 v254, s2, 10
	s_or_b32 s2, s5, 2
	v_writelane_b32 v254, s2, 11
	s_add_i32 s2, s5, 4
	v_writelane_b32 v254, s2, 12
	s_xor_b32 s2, s40, 7
	s_add_i32 s2, s2, s52
	v_writelane_b32 v254, s2, 13
	s_lshl_b32 s2, s8, 3
	s_sub_i32 s2, 0, s2
	v_writelane_b32 v254, s2, 14
	s_lshl_b32 s2, s8, 4
	s_lshl_b32 s3, s52, 4
	v_writelane_b32 v254, s3, 15
	s_sub_i32 s3, s3, s2
	v_writelane_b32 v254, s3, 16
	s_mov_b32 s4, s60
	v_writelane_b32 v254, s4, 17
	s_sub_i32 s2, s60, s2
	s_xor_b64 s[0:1], s[0:1], -1
	v_writelane_b32 v254, s5, 18
	v_writelane_b32 v254, s2, 19
	v_writelane_b32 v254, s0, 20
	s_ashr_i32 s11, s10, 31
	v_writelane_b32 v252, s6, 13
	v_writelane_b32 v254, s1, 21
	v_writelane_b32 v254, s42, 22
	s_add_i32 s0, s42, s52
	v_writelane_b32 v252, s7, 14
	v_writelane_b32 v254, s43, 23
	v_writelane_b32 v254, s0, 24
	s_lshl_b32 s0, s40, 6
	v_writelane_b32 v254, s0, 25
	s_lshl_b32 s0, s52, 6
	v_writelane_b32 v254, s0, 26
	s_lshl_b32 s0, s40, 4
	v_writelane_b32 v254, s0, 27
	v_writelane_b32 v254, s39, 28
	s_lshl_b32 s0, s39, 7
	v_writelane_b32 v254, s0, 29
	s_lshl_b32 s0, s52, 7
	v_writelane_b32 v254, s0, 30
	s_add_i32 s0, 0, 0x20000
	v_writelane_b32 v254, s0, 31
	s_add_i32 s0, 0, 0x20004
	v_writelane_b32 v254, s0, 32
	s_add_i32 s0, 0, 0x14c00
	v_writelane_b32 v254, s0, 33
	s_mov_b32 s0, s10
	v_writelane_b32 v254, s0, 34
	v_mov_b32_e32 v1, 0
	s_mov_b32 s20, 0
	v_writelane_b32 v254, s1, 35
	s_lshl_b64 s[0:1], s[10:11], 19
	v_writelane_b32 v254, s0, 36
	s_mov_b64 s[60:61], 0x40000
	s_mov_b64 s[72:73], 0x20080
	v_writelane_b32 v254, s1, 37
	s_lshl_b64 s[0:1], s[52:53], 11
	v_writelane_b32 v254, s0, 38
	s_mov_b64 s[48:49], 0x40080
	s_mov_b64 s[66:67], 0x60080
	v_writelane_b32 v254, s1, 39
	s_lshl_b64 s[0:1], s[52:53], 10
	v_writelane_b32 v254, s0, 40
	s_mov_b64 s[92:93], 0x58000
	s_mov_b64 s[4:5], 0xb0000
	v_writelane_b32 v254, s1, 41
	s_lshl_b64 s[0:1], s[40:41], 12
	v_writelane_b32 v254, s0, 42
	s_mov_b64 s[96:97], 0x108000
	s_mov_b64 s[54:55], 0xb0080
	v_writelane_b32 v254, s1, 43
	s_lshl_b64 s[0:1], s[52:53], 14
	v_writelane_b32 v254, s0, 44
	s_mov_b64 s[80:81], 0x108080
	s_mov_b64 s[82:83], 0x18000
	v_writelane_b32 v254, s1, 45
	s_lshl_b64 s[0:1], s[52:53], 12
	v_writelane_b32 v254, s0, 46
	s_mov_b64 s[2:3], 0x18080
	s_mov_b64 s[50:51], 0x2000
	v_writelane_b32 v254, s1, 47
	v_writelane_b32 v254, s86, 48
	v_writelane_b32 v254, s84, 49
	s_mov_b64 s[0:1], 0x58080
	v_mbcnt_lo_u32_b32 v0, -1, 0
	v_mbcnt_hi_u32_b32 v0, -1, v0
	s_nop 0
	v_writelane_b32 v254, s85, 50
	v_writelane_b32 v254, s33, 51
	s_branch .LBB0_272

; DI void rms_row2_bf16(const float* xa, const float* xb, bool hasb, const float* g, bf16_t* oa, bf16_t* ob, int lane) {
;     f32x4 va[4], vb[4]; float sa = 0.f, sb = 0.f;
; #pragma unroll
;     for (int j = 0; j < 4; ++j) { va[j] = ((const f32x4*)xa)[lane + 64 * j]; vb[j] = hasb ? ((const f32x4*)xb)[lane + 64 * j] : (f32x4){0.f, 0.f, 0.f, 0.f}; }
; __global__ void __launch_bounds__(512, 2) fwd_mega(Params P) {
;     ...
;         if (g + 1 < NGRP && bid >= G / 2) { const size_t n0 = (size_t)(g + 1) * MG;
;             const int st_ = (G - G / 2) * 8;
;             for (int m = (bid - G / 2) * 8 + wid; m < MG; m += 2 * st_) rms_row2_bf16(pp->in[0] + (n0 + m) * 1024, pp->in[0] + (n0 + m + st_) * 1024, m + st_ < MG, pp->in[7], WSB(WS_XN) + (size_t)m * 1024, WSB(WS_XN) + (size_t)(m + st_) * 1024, lane); }
.LBB0_1791:
	v_readlane_b32 s6, v252, 0
	v_readlane_b32 s7, v252, 1
	s_load_dwordx4 s[16:19], s[6:7], 0xe0
	v_readlane_b32 s8, v254, 54
	s_add_i32 s87, s8, 1
	v_readlane_b32 s8, v252, 50
	v_readlane_b32 s10, v254, 61
	v_readlane_b32 s9, v252, 51
	v_readlane_b32 s11, v254, 62
	s_or_b64 s[8:9], s[10:11], s[8:9]
	s_and_b64 vcc, exec, s[8:9]
	v_mbcnt_lo_u32_b32 v50, -1, 0
	v_mbcnt_hi_u32_b32 v50, -1, v50
	s_cbranch_vccnz .LBB0_1805
	v_readlane_b32 s8, v252, 7
	s_lshl_b32 s9, s8, 3
	s_and_b32 s9, s9, 0xf8
	s_lshr_b32 s8, s8, 5
	s_add_i32 s8, s9, s8
	v_readlane_b32 s9, v254, 54
	s_cmp_eq_u32 s9, 2
	s_movk_i32 s9, 0xf8
	s_cselect_b32 s9, 0xd4, s9
	s_cmp_ge_u32 s8, s9
	s_cbranch_scc1 .LBB0_1805
	v_and_b32_e32 v0, 64, v226
	v_add_u32_e32 v4, 64, v0
	v_xor_b32_e32 v0, 1, v226
	v_cmp_lt_i32_e32 vcc, v0, v4
	v_xor_b32_e32 v5, 2, v226
	s_load_dwordx2 s[8:9], s[6:7], 0x38
	s_nop 0
	s_load_dwordx2 s[6:7], s[6:7], 0x0
	v_cndmask_b32_e32 v0, v226, v0, vcc
	v_cmp_lt_i32_e32 vcc, v5, v4
	v_ashrrev_i32_e32 v51, 31, v50
	v_lshlrev_b64 v[2:3], 4, v[50:51]
	v_cndmask_b32_e32 v5, v226, v5, vcc
	v_lshlrev_b32_e32 v58, 2, v5
	v_xor_b32_e32 v5, 4, v226
	v_cmp_lt_i32_e32 vcc, v5, v4
	s_waitcnt lgkmcnt(0)
	v_lshl_add_u64 v[52:53], s[8:9], 0, v[2:3]
	v_lshl_add_u64 v[54:55], s[6:7], 0, v[2:3]
	v_cndmask_b32_e32 v5, v226, v5, vcc
	v_lshlrev_b32_e32 v59, 2, v5
	v_xor_b32_e32 v5, 8, v226
	v_cmp_lt_i32_e32 vcc, v5, v4
	v_lshl_add_u64 v[2:3], v[50:51], 3, s[18:19]
	s_mov_b64 s[8:9], 0x5ec2800
	v_cndmask_b32_e32 v5, v226, v5, vcc
	v_lshlrev_b32_e32 v60, 2, v5
	v_xor_b32_e32 v5, 16, v226
	v_cmp_lt_i32_e32 vcc, v5, v4
	v_lshl_add_u64 v[56:57], v[2:3], 0, s[8:9]
	v_readlane_b32 s8, v252, 17
	v_cndmask_b32_e32 v5, v226, v5, vcc
	v_lshlrev_b32_e32 v61, 2, v5
	v_xor_b32_e32 v5, 32, v226
	v_cmp_lt_i32_e32 vcc, v5, v4
	v_readlane_b32 s9, v252, 18
	s_lshl_b32 s20, s87, 14
	v_cndmask_b32_e32 v4, v226, v5, vcc
	v_lshlrev_b32_e32 v0, 2, v0
	v_lshlrev_b32_e32 v62, 2, v4
	v_readlane_b32 s8, v252, 7
	s_lshl_b32 s9, s8, 3
	s_and_b32 s9, s9, 0xf8
	s_lshr_b32 s8, s8, 5
	s_add_i32 s8, s9, s8
	s_lshl_b32 s21, s8, 3
	v_readlane_b32 s8, v252, 6
	s_lshr_b32 s8, s8, 6
	s_add_i32 s21, s21, s8
	v_readlane_b32 s9, v254, 14
	s_branch .LBB0_1795
.LBB0_1794:
	v_readlane_b32 s8, v254, 54
	s_cmp_eq_u32 s8, 2
	s_movk_i32 s8, 0x780
	s_cselect_b32 s8, 0x540, s8
	s_add_i32 s21, s21, s8
	v_readlane_b32 s9, v254, 14
	s_add_i32 s8, s9, s21
	s_cmpk_lt_i32 s8, 0x4000
	s_cbranch_scc0 .LBB0_1805
.LBB0_1795:
	s_add_i32 s10, s9, s21
	s_ashr_i32 s11, s10, 31
	s_add_u32 s8, s10, s20
	s_addc_u32 s9, s11, 0
	s_lshl_b64 s[12:13], s[8:9], 12
	v_lshl_add_u64 v[12:13], v[54:55], 0, s[12:13]
	global_load_dwordx4 v[30:33], v[12:13], off
	v_readlane_b32 s12, v254, 54
	s_cmp_eq_u32 s12, 2
	s_movk_i32 s12, 0x3c0
	s_cselect_b32 s12, 0x2a0, s12
	s_add_u32 s8, s8, s12
	s_addc_u32 s9, s9, 0
	s_lshl_b64 s[8:9], s[8:9], 12
	s_add_u32 s12, s6, s8
	s_addc_u32 s13, s7, s9
	v_readlane_b32 s8, v254, 54
	s_cmp_eq_u32 s8, 2
	s_movk_i32 s8, 0xffc0
	s_cselect_b32 s8, 0xfffffea0, s8
	s_add_i32 s8, s8, s21
	s_cmpk_lt_i32 s8, 0x4000
	s_cselect_b64 s[14:15], -1, 0
	s_cmpk_gt_i32 s8, 0x3fff
	v_mov_b32_e32 v2, 0
	v_lshl_add_u64 v[18:19], v[50:51], 4, s[12:13]
	v_mov_b32_e32 v6, 0
	v_mov_b32_e32 v7, 0
	v_mov_b32_e32 v8, 0
	v_mov_b32_e32 v9, 0
	s_cbranch_scc1 .LBB0_1797
	global_load_dwordx4 v[6:9], v[18:19], off
